# next-phase prefetch in seam slack: waves 1-7 touch the next GEMM phase's first weight tile (K-tiles 0-1) into L2 via LDS-DMA dword right after the seam's first barrier
# speedup vs baseline: 1.0041x; 1.0041x over previous
; __device__ __forceinline__ unsigned xb_ld(unsigned* p)              { return __hip_atomic_load(p, __ATOMIC_RELAXED, __HIP_MEMORY_SCOPE_AGENT); }
; __device__ __forceinline__ unsigned xb_add(unsigned* p, unsigned v) { return __hip_atomic_fetch_add(p, v, __ATOMIC_RELAXED, __HIP_MEMORY_SCOPE_AGENT); }
; #define XB_SPIN(cond, bar) do { unsigned _sp = 0; while (cond) { __builtin_amdgcn_s_sleep(1); \
;     if ((++_sp & 255u) == 0u) { if (xb_ld(&(bar)[XB_TMO])) break; if (_sp > XB_SPIN_CAP) { atomicAdd(&(bar)[XB_TMO], 1u); break; } } } } while (0)
; __device__ __forceinline__ void team_barrier(const Team& T) {
;     asm volatile("s_waitcnt vmcnt(0)" ::: "memory");
;     __syncthreads();
;     if (threadIdx.x == 0) {
;         __builtin_amdgcn_s_waitcnt(0);
;         if (!T.same) { __builtin_amdgcn_fence(__ATOMIC_RELEASE, "agent"); asm volatile("s_waitcnt vmcnt(0)" ::: "memory"); }
;         const unsigned old = xb_add(T.cnt, 1u), target = (old / 4u + 1u) * 4u;
;         XB_SPIN(xb_ld(T.cnt) < target, T.tmo);
.LBB0_468:
	s_and_b64 vcc, exec, s[0:1]
	s_cbranch_vccz .LBB0_486
	s_waitcnt vmcnt(0)
	s_barrier
	v_readfirstlane_b32 s98, v200
	s_cmp_lt_u32 s98, 64
	s_cbranch_scc1 .Lwpf_skip_0
	v_lshrrev_b32_e32 v0, 1, v200
	v_and_b32_e32 v1, 1, v200
	v_mul_u32_u24_e32 v0, 0x2c00, v0
	v_lshl_add_u32 v0, v1, 7, v0
	s_lshr_b32 s98, s2, 6
	s_mul_i32 s98, s98, 0x2c0000
	s_add_u32 s98, s98, 0x29000000
	s_add_u32 s98, s74, s98
	s_addc_u32 s99, s75, 0
	s_mov_b32 m0, 0x20c00
	s_nop 0
	global_load_lds_dword v0, s[98:99]
.Lwpf_skip_0:
	s_and_saveexec_b64 s[10:11], s[6:7]
	s_cbranch_execz .LBB0_485
	v_readlane_b32 s0, v254, 15
	v_readlane_b32 s1, v254, 16
	s_andn2_b64 vcc, exec, s[0:1]
	s_waitcnt vmcnt(0) expcnt(0) lgkmcnt(0)
	s_cbranch_vccnz .LBB0_472
	buffer_wbl2 sc1
	s_waitcnt vmcnt(0)

; __device__ __forceinline__ unsigned xb_ld(unsigned* p)              { return __hip_atomic_load(p, __ATOMIC_RELAXED, __HIP_MEMORY_SCOPE_AGENT); }
; __device__ __forceinline__ unsigned xb_add(unsigned* p, unsigned v) { return __hip_atomic_fetch_add(p, v, __ATOMIC_RELAXED, __HIP_MEMORY_SCOPE_AGENT); }
; #define XB_SPIN(cond, bar) do { unsigned _sp = 0; while (cond) { __builtin_amdgcn_s_sleep(1); \
;     if ((++_sp & 255u) == 0u) { if (xb_ld(&(bar)[XB_TMO])) break; if (_sp > XB_SPIN_CAP) { atomicAdd(&(bar)[XB_TMO], 1u); break; } } } } while (0)
; __device__ __forceinline__ void team_barrier(const Team& T) {
;     asm volatile("s_waitcnt vmcnt(0)" ::: "memory");
;     __syncthreads();
;     if (threadIdx.x == 0) {
;         __builtin_amdgcn_s_waitcnt(0);
;         if (!T.same) { __builtin_amdgcn_fence(__ATOMIC_RELEASE, "agent"); asm volatile("s_waitcnt vmcnt(0)" ::: "memory"); }
;         const unsigned old = xb_add(T.cnt, 1u), target = (old / 4u + 1u) * 4u;
;         XB_SPIN(xb_ld(T.cnt) < target, T.tmo);
.LBB0_589:
	s_and_b64 vcc, exec, s[0:1]
	s_cbranch_vccz .LBB0_607
	s_waitcnt vmcnt(0)
	s_barrier
	v_readfirstlane_b32 s98, v200
	s_cmp_lt_u32 s98, 64
	s_cbranch_scc1 .Lwpf_skip_1
	v_lshrrev_b32_e32 v0, 1, v200
	v_and_b32_e32 v1, 1, v200
	v_mul_u32_u24_e32 v0, 0x1000, v0
	v_lshl_add_u32 v0, v1, 7, v0
	s_lshr_b32 s98, s2, 6
	s_mul_i32 s98, s98, 0x100000
	s_add_u32 s98, s98, 0x2fa00000
	s_add_u32 s98, s74, s98
	s_addc_u32 s99, s75, 0
	s_mov_b32 m0, 0x20c00
	s_nop 0
	global_load_lds_dword v0, s[98:99]

; __device__ __forceinline__ unsigned xb_ld(unsigned* p)              { return __hip_atomic_load(p, __ATOMIC_RELAXED, __HIP_MEMORY_SCOPE_AGENT); }
; __device__ __forceinline__ unsigned xb_add(unsigned* p, unsigned v) { return __hip_atomic_fetch_add(p, v, __ATOMIC_RELAXED, __HIP_MEMORY_SCOPE_AGENT); }
; #define XB_SPIN(cond, bar) do { unsigned _sp = 0; while (cond) { __builtin_amdgcn_s_sleep(1); \
;     if ((++_sp & 255u) == 0u) { if (xb_ld(&(bar)[XB_TMO])) break; if (_sp > XB_SPIN_CAP) { atomicAdd(&(bar)[XB_TMO], 1u); break; } } } } while (0)
; __device__ __forceinline__ void team_barrier(const Team& T) {
;     asm volatile("s_waitcnt vmcnt(0)" ::: "memory");
;     __syncthreads();
;     if (threadIdx.x == 0) {
;         __builtin_amdgcn_s_waitcnt(0);
;         if (!T.same) { __builtin_amdgcn_fence(__ATOMIC_RELEASE, "agent"); asm volatile("s_waitcnt vmcnt(0)" ::: "memory"); }
;         const unsigned old = xb_add(T.cnt, 1u), target = (old / 4u + 1u) * 4u;
;         XB_SPIN(xb_ld(T.cnt) < target, T.tmo);
.LBB0_918:
	s_and_b64 vcc, exec, s[0:1]
	s_cbranch_vccz .LBB0_936
	s_waitcnt vmcnt(0)
	s_barrier
	v_readfirstlane_b32 s98, v200
	s_cmp_lt_u32 s98, 64
	s_cbranch_scc1 .Lwpf_skip_2
	v_lshrrev_b32_e32 v0, 1, v200
	v_and_b32_e32 v1, 1, v200
	v_mul_u32_u24_e32 v0, 0x1000, v0
	v_lshl_add_u32 v0, v1, 7, v0
	s_lshr_b32 s98, s2, 6
	s_mul_i32 s98, s98, 0x100000
	s_add_u32 s98, s98, 0x23800000
	s_add_u32 s98, s74, s98
	s_addc_u32 s99, s75, 0
	s_mov_b32 m0, 0x20c00
	s_nop 0
	global_load_lds_dword v0, s[98:99]

; __device__ __forceinline__ unsigned xb_ld(unsigned* p)              { return __hip_atomic_load(p, __ATOMIC_RELAXED, __HIP_MEMORY_SCOPE_AGENT); }
; __device__ __forceinline__ unsigned xb_add(unsigned* p, unsigned v) { return __hip_atomic_fetch_add(p, v, __ATOMIC_RELAXED, __HIP_MEMORY_SCOPE_AGENT); }
; #define XB_SPIN(cond, bar) do { unsigned _sp = 0; while (cond) { __builtin_amdgcn_s_sleep(1); \
;     if ((++_sp & 255u) == 0u) { if (xb_ld(&(bar)[XB_TMO])) break; if (_sp > XB_SPIN_CAP) { atomicAdd(&(bar)[XB_TMO], 1u); break; } } } } while (0)
; __device__ __forceinline__ void team_barrier(const Team& T) {
;     asm volatile("s_waitcnt vmcnt(0)" ::: "memory");
;     __syncthreads();
;     if (threadIdx.x == 0) {
;         __builtin_amdgcn_s_waitcnt(0);
;         if (!T.same) { __builtin_amdgcn_fence(__ATOMIC_RELEASE, "agent"); asm volatile("s_waitcnt vmcnt(0)" ::: "memory"); }
;         const unsigned old = xb_add(T.cnt, 1u), target = (old / 4u + 1u) * 4u;
;         XB_SPIN(xb_ld(T.cnt) < target, T.tmo);
.LBB0_1071:
	s_and_b64 vcc, exec, s[0:1]
	s_cbranch_vccz .LBB0_1089
	s_waitcnt vmcnt(0)
	s_barrier
	v_readfirstlane_b32 s98, v200
	s_cmp_lt_u32 s98, 64
	s_cbranch_scc1 .Lwpf_skip_3
	v_lshrrev_b32_e32 v0, 1, v200
	v_and_b32_e32 v1, 1, v200
	v_mul_u32_u24_e32 v0, 0x2c00, v0
	v_lshl_add_u32 v0, v1, 7, v0
	s_lshr_b32 s98, s2, 6
	s_mul_i32 s98, s98, 0x2c0000
	s_add_u32 s98, s98, 0x2bc00000
	s_add_u32 s98, s74, s98
	s_addc_u32 s99, s75, 0
	s_mov_b32 m0, 0x20c00
	s_nop 0
	global_load_lds_dword v0, s[98:99]

; __device__ __forceinline__ unsigned xb_ld(unsigned* p)              { return __hip_atomic_load(p, __ATOMIC_RELAXED, __HIP_MEMORY_SCOPE_AGENT); }
; __device__ __forceinline__ unsigned xb_add(unsigned* p, unsigned v) { return __hip_atomic_fetch_add(p, v, __ATOMIC_RELAXED, __HIP_MEMORY_SCOPE_AGENT); }
; #define XB_SPIN(cond, bar) do { unsigned _sp = 0; while (cond) { __builtin_amdgcn_s_sleep(1); \
;     if ((++_sp & 255u) == 0u) { if (xb_ld(&(bar)[XB_TMO])) break; if (_sp > XB_SPIN_CAP) { atomicAdd(&(bar)[XB_TMO], 1u); break; } } } } while (0)
; __device__ __forceinline__ void team_barrier(const Team& T) {
;     asm volatile("s_waitcnt vmcnt(0)" ::: "memory");
;     __syncthreads();
;     if (threadIdx.x == 0) {
;         __builtin_amdgcn_s_waitcnt(0);
;         if (!T.same) { __builtin_amdgcn_fence(__ATOMIC_RELEASE, "agent"); asm volatile("s_waitcnt vmcnt(0)" ::: "memory"); }
;         const unsigned old = xb_add(T.cnt, 1u), target = (old / 4u + 1u) * 4u;
;         XB_SPIN(xb_ld(T.cnt) < target, T.tmo);
.LBB0_1192:
	s_and_b64 vcc, exec, s[0:1]
	s_cbranch_vccz .LBB0_1210
	s_waitcnt vmcnt(0)
	s_barrier
	v_readfirstlane_b32 s98, v200
	s_cmp_lt_u32 s98, 64
	s_cbranch_scc1 .Lwpf_skip_4
	v_lshrrev_b32_e32 v0, 1, v200
	v_and_b32_e32 v1, 1, v200
	v_mul_u32_u24_e32 v0, 0x1000, v0
	v_lshl_add_u32 v0, v1, 7, v0
	s_lshr_b32 s98, s2, 6
	s_mul_i32 s98, s98, 0x100000
	s_add_u32 s98, s98, 0x2e800000
	s_add_u32 s98, s74, s98
	s_addc_u32 s99, s75, 0
	s_mov_b32 m0, 0x20c00
	s_nop 0
	global_load_lds_dword v0, s[98:99]

; __device__ __forceinline__ unsigned xb_ld(unsigned* p)              { return __hip_atomic_load(p, __ATOMIC_RELAXED, __HIP_MEMORY_SCOPE_AGENT); }
; __device__ __forceinline__ unsigned xb_add(unsigned* p, unsigned v) { return __hip_atomic_fetch_add(p, v, __ATOMIC_RELAXED, __HIP_MEMORY_SCOPE_AGENT); }
; #define XB_SPIN(cond, bar) do { unsigned _sp = 0; while (cond) { __builtin_amdgcn_s_sleep(1); \
;     if ((++_sp & 255u) == 0u) { if (xb_ld(&(bar)[XB_TMO])) break; if (_sp > XB_SPIN_CAP) { atomicAdd(&(bar)[XB_TMO], 1u); break; } } } } while (0)
; __device__ __forceinline__ void team_barrier(const Team& T) {
;     asm volatile("s_waitcnt vmcnt(0)" ::: "memory");
;     __syncthreads();
;     if (threadIdx.x == 0) {
;         __builtin_amdgcn_s_waitcnt(0);
;         if (!T.same) { __builtin_amdgcn_fence(__ATOMIC_RELEASE, "agent"); asm volatile("s_waitcnt vmcnt(0)" ::: "memory"); }
;         const unsigned old = xb_add(T.cnt, 1u), target = (old / 4u + 1u) * 4u;
;         XB_SPIN(xb_ld(T.cnt) < target, T.tmo);
.LBB0_1345:
	s_and_b64 vcc, exec, s[0:1]
	s_cbranch_vccz .LBB0_1363
	s_waitcnt vmcnt(0)
	s_barrier
	v_readfirstlane_b32 s98, v200
	s_cmp_lt_u32 s98, 64
	s_cbranch_scc1 .Lwpf_skip_5
	v_lshrrev_b32_e32 v0, 1, v200
	v_and_b32_e32 v1, 1, v200
	v_mul_u32_u24_e32 v0, 0x1000, v0
	v_lshl_add_u32 v0, v1, 7, v0
	s_lshr_b32 s98, s2, 6
	s_mul_i32 s98, s98, 0x100000
	s_add_u32 s98, s98, 0x20c00000
	s_add_u32 s98, s74, s98
	s_addc_u32 s99, s75, 0
	s_mov_b32 m0, 0x20c00
	s_nop 0
	global_load_lds_dword v0, s[98:99]

; __device__ __forceinline__ unsigned xb_ld(unsigned* p)              { return __hip_atomic_load(p, __ATOMIC_RELAXED, __HIP_MEMORY_SCOPE_AGENT); }
; __device__ __forceinline__ unsigned xb_add(unsigned* p, unsigned v) { return __hip_atomic_fetch_add(p, v, __ATOMIC_RELAXED, __HIP_MEMORY_SCOPE_AGENT); }
; #define XB_SPIN(cond, bar) do { unsigned _sp = 0; while (cond) { __builtin_amdgcn_s_sleep(1); \
;     if ((++_sp & 255u) == 0u) { if (xb_ld(&(bar)[XB_TMO])) break; if (_sp > XB_SPIN_CAP) { atomicAdd(&(bar)[XB_TMO], 1u); break; } } } } while (0)
; __device__ __forceinline__ void team_barrier(const Team& T) {
;     asm volatile("s_waitcnt vmcnt(0)" ::: "memory");
;     __syncthreads();
;     if (threadIdx.x == 0) {
;         __builtin_amdgcn_s_waitcnt(0);
;         if (!T.same) { __builtin_amdgcn_fence(__ATOMIC_RELEASE, "agent"); asm volatile("s_waitcnt vmcnt(0)" ::: "memory"); }
;         const unsigned old = xb_add(T.cnt, 1u), target = (old / 4u + 1u) * 4u;
;         XB_SPIN(xb_ld(T.cnt) < target, T.tmo);
.LBB0_1474:
	s_and_b64 vcc, exec, s[0:1]
	s_cbranch_vccz .LBB0_1492
	s_waitcnt vmcnt(0)
	s_barrier
	v_readfirstlane_b32 s98, v200
	s_cmp_lt_u32 s98, 64
	s_cbranch_scc1 .Lwpf_skip_6
	v_lshrrev_b32_e32 v0, 1, v200
	v_and_b32_e32 v1, 1, v200
	v_mul_u32_u24_e32 v0, 0x2c00, v0
	v_lshl_add_u32 v0, v1, 7, v0
	s_lshr_b32 s98, s2, 6
	s_mul_i32 s98, s98, 0x2c0000
	s_add_u32 s98, s98, 0x2a600000
	s_add_u32 s98, s74, s98
	s_addc_u32 s99, s75, 0
	s_mov_b32 m0, 0x20c00
	s_nop 0
	global_load_lds_dword v0, s[98:99]

; __device__ __forceinline__ unsigned xb_ld(unsigned* p)              { return __hip_atomic_load(p, __ATOMIC_RELAXED, __HIP_MEMORY_SCOPE_AGENT); }
; __device__ __forceinline__ unsigned xb_add(unsigned* p, unsigned v) { return __hip_atomic_fetch_add(p, v, __ATOMIC_RELAXED, __HIP_MEMORY_SCOPE_AGENT); }
; #define XB_SPIN(cond, bar) do { unsigned _sp = 0; while (cond) { __builtin_amdgcn_s_sleep(1); \
;     if ((++_sp & 255u) == 0u) { if (xb_ld(&(bar)[XB_TMO])) break; if (_sp > XB_SPIN_CAP) { atomicAdd(&(bar)[XB_TMO], 1u); break; } } } } while (0)
; __device__ __forceinline__ void team_barrier(const Team& T) {
;     asm volatile("s_waitcnt vmcnt(0)" ::: "memory");
;     __syncthreads();
;     if (threadIdx.x == 0) {
;         __builtin_amdgcn_s_waitcnt(0);
;         if (!T.same) { __builtin_amdgcn_fence(__ATOMIC_RELEASE, "agent"); asm volatile("s_waitcnt vmcnt(0)" ::: "memory"); }
;         const unsigned old = xb_add(T.cnt, 1u), target = (old / 4u + 1u) * 4u;
;         XB_SPIN(xb_ld(T.cnt) < target, T.tmo);
.LBB0_1595:
	s_and_b64 vcc, exec, s[0:1]
	s_cbranch_vccz .LBB0_1613
	s_waitcnt vmcnt(0)
	s_barrier
	v_readfirstlane_b32 s98, v200
	s_cmp_lt_u32 s98, 64
	s_cbranch_scc1 .Lwpf_skip_7
	v_lshrrev_b32_e32 v0, 1, v200
	v_and_b32_e32 v1, 1, v200
	v_mul_u32_u24_e32 v0, 0x1000, v0
	v_lshl_add_u32 v0, v1, 7, v0
	s_lshr_b32 s98, s2, 6
	s_mul_i32 s98, s98, 0x100000
	s_add_u32 s98, s98, 0x32a00000
	s_add_u32 s98, s74, s98
	s_addc_u32 s99, s75, 0
	s_mov_b32 m0, 0x20c00
	s_nop 0
	global_load_lds_dword v0, s[98:99]

; __device__ __forceinline__ unsigned xb_ld(unsigned* p)              { return __hip_atomic_load(p, __ATOMIC_RELAXED, __HIP_MEMORY_SCOPE_AGENT); }
; __device__ __forceinline__ unsigned xb_add(unsigned* p, unsigned v) { return __hip_atomic_fetch_add(p, v, __ATOMIC_RELAXED, __HIP_MEMORY_SCOPE_AGENT); }
; #define XB_SPIN(cond, bar) do { unsigned _sp = 0; while (cond) { __builtin_amdgcn_s_sleep(1); \
;     if ((++_sp & 255u) == 0u) { if (xb_ld(&(bar)[XB_TMO])) break; if (_sp > XB_SPIN_CAP) { atomicAdd(&(bar)[XB_TMO], 1u); break; } } } } while (0)
; __device__ __forceinline__ void team_barrier(const Team& T) {
;     asm volatile("s_waitcnt vmcnt(0)" ::: "memory");
;     __syncthreads();
;     if (threadIdx.x == 0) {
;         __builtin_amdgcn_s_waitcnt(0);
;         if (!T.same) { __builtin_amdgcn_fence(__ATOMIC_RELEASE, "agent"); asm volatile("s_waitcnt vmcnt(0)" ::: "memory"); }
;         const unsigned old = xb_add(T.cnt, 1u), target = (old / 4u + 1u) * 4u;
;         XB_SPIN(xb_ld(T.cnt) < target, T.tmo);
.LBB0_1911:
	s_and_b64 vcc, exec, s[0:1]
	s_cbranch_vccz .LBB0_1929
	s_waitcnt vmcnt(0)
	s_barrier
	v_readfirstlane_b32 s98, v200
	s_cmp_lt_u32 s98, 64
	s_cbranch_scc1 .Lwpf_skip_8
	v_lshrrev_b32_e32 v0, 1, v200
	v_and_b32_e32 v1, 1, v200
	v_mul_u32_u24_e32 v0, 0x1000, v0
	v_lshl_add_u32 v0, v1, 7, v0
	s_lshr_b32 s98, s2, 6
	s_mul_i32 s98, s98, 0x100000
	s_add_u32 s98, s98, 0x26400000
	s_add_u32 s98, s74, s98
	s_addc_u32 s99, s75, 0
	s_mov_b32 m0, 0x20c00
	s_nop 0
	global_load_lds_dword v0, s[98:99]

; __device__ __forceinline__ unsigned xb_ld(unsigned* p)              { return __hip_atomic_load(p, __ATOMIC_RELAXED, __HIP_MEMORY_SCOPE_AGENT); }
; __device__ __forceinline__ unsigned xb_add(unsigned* p, unsigned v) { return __hip_atomic_fetch_add(p, v, __ATOMIC_RELAXED, __HIP_MEMORY_SCOPE_AGENT); }
; #define XB_SPIN(cond, bar) do { unsigned _sp = 0; while (cond) { __builtin_amdgcn_s_sleep(1); \
;     if ((++_sp & 255u) == 0u) { if (xb_ld(&(bar)[XB_TMO])) break; if (_sp > XB_SPIN_CAP) { atomicAdd(&(bar)[XB_TMO], 1u); break; } } } } while (0)
; __device__ __forceinline__ void team_barrier(const Team& T) {
;     asm volatile("s_waitcnt vmcnt(0)" ::: "memory");
;     __syncthreads();
;     if (threadIdx.x == 0) {
;         __builtin_amdgcn_s_waitcnt(0);
;         if (!T.same) { __builtin_amdgcn_fence(__ATOMIC_RELEASE, "agent"); asm volatile("s_waitcnt vmcnt(0)" ::: "memory"); }
;         const unsigned old = xb_add(T.cnt, 1u), target = (old / 4u + 1u) * 4u;
;         XB_SPIN(xb_ld(T.cnt) < target, T.tmo);
.LBB0_2064:
	s_and_b64 vcc, exec, s[0:1]
	s_cbranch_vccz .LBB0_2082
	s_waitcnt vmcnt(0)
	s_barrier
	v_readfirstlane_b32 s98, v200
	s_cmp_lt_u32 s98, 64
	s_cbranch_scc1 .Lwpf_skip_9
	v_lshrrev_b32_e32 v0, 1, v200
	v_and_b32_e32 v1, 1, v200
	v_mul_u32_u24_e32 v0, 0x2c00, v0
	v_lshl_add_u32 v0, v1, 7, v0
	s_lshr_b32 s98, s2, 6
	s_mul_i32 s98, s98, 0x2c0000
	s_add_u32 s98, s98, 0x2d200000
	s_add_u32 s98, s74, s98
	s_addc_u32 s99, s75, 0
	s_mov_b32 m0, 0x20c00
	s_nop 0
	global_load_lds_dword v0, s[98:99]

; __device__ __forceinline__ unsigned xb_ld(unsigned* p)              { return __hip_atomic_load(p, __ATOMIC_RELAXED, __HIP_MEMORY_SCOPE_AGENT); }
; __device__ __forceinline__ unsigned xb_add(unsigned* p, unsigned v) { return __hip_atomic_fetch_add(p, v, __ATOMIC_RELAXED, __HIP_MEMORY_SCOPE_AGENT); }
; #define XB_SPIN(cond, bar) do { unsigned _sp = 0; while (cond) { __builtin_amdgcn_s_sleep(1); \
;     if ((++_sp & 255u) == 0u) { if (xb_ld(&(bar)[XB_TMO])) break; if (_sp > XB_SPIN_CAP) { atomicAdd(&(bar)[XB_TMO], 1u); break; } } } } while (0)
; __device__ __forceinline__ void team_barrier(const Team& T) {
;     asm volatile("s_waitcnt vmcnt(0)" ::: "memory");
;     __syncthreads();
;     if (threadIdx.x == 0) {
;         __builtin_amdgcn_s_waitcnt(0);
;         if (!T.same) { __builtin_amdgcn_fence(__ATOMIC_RELEASE, "agent"); asm volatile("s_waitcnt vmcnt(0)" ::: "memory"); }
;         const unsigned old = xb_add(T.cnt, 1u), target = (old / 4u + 1u) * 4u;
;         XB_SPIN(xb_ld(T.cnt) < target, T.tmo);
.LBB0_2185:
	s_and_b64 vcc, exec, s[0:1]
	s_cbranch_vccz .LBB0_2203
	s_waitcnt vmcnt(0)
	s_barrier
	v_readfirstlane_b32 s98, v200
	s_cmp_lt_u32 s98, 64
	s_cbranch_scc1 .Lwpf_skip_10
	v_lshrrev_b32_e32 v0, 1, v200
	v_and_b32_e32 v1, 1, v200
	v_mul_u32_u24_e32 v0, 0x1000, v0
	v_lshl_add_u32 v0, v1, 7, v0
	s_lshr_b32 s98, s2, 6
	s_mul_i32 s98, s98, 0x100000
	s_add_u32 s98, s98, 0x2f000000
	s_add_u32 s98, s74, s98
	s_addc_u32 s99, s75, 0
	s_mov_b32 m0, 0x20c00
	s_nop 0
	global_load_lds_dword v0, s[98:99]
